# also static s_setprio 1 for waves 0-3 in the NSA2 / MoBA attention units
# baseline (speedup 1.0000x reference)
.Lnsa2_skipfill:
	v_readfirstlane_b32 s92, v200
	s_lshr_b32 s92, s92, 8
	s_and_b32 s92, s92, 1
	s_mul_i32 s93, s92, 0xb00
	s_add_i32 s93, s93, 0x1d000
	s_add_i32 s92, s93, 148
	s_add_i32 s94, s93, 276
	s_add_i32 s95, s93, 192
	s_add_i32 s96, s93, 320
	v_readfirstlane_b32 s90, v200
	s_cmp_ge_u32 s90, 0x100
	s_cbranch_scc1 .Lprio_nsa2
	s_setprio 1
.Lprio_nsa2:
	s_xor_b64 s[50:51], s[2:3], -1
	s_and_b64 s[0:1], s[2:3], exec
	s_cselect_b32 s61, s82, s80
	s_lshl_b32 s60, s61, 8
	v_and_b32_e32 v181, 0xc0, v2
	v_and_b32_e32 v151, 31, v2
	v_or_b32_e32 v182, s60, v181
	v_ashrrev_i32_e32 v3, 8, v2
	v_or_b32_e32 v0, v182, v151
	v_add_u32_e32 v185, s81, v3
	v_lshl_add_u64 v[146:147], s[34:35], 0, v[0:1]
	v_mad_u64_u32 v[4:5], s[0:1], v146, s73, v[138:139]
	v_lshlrev_b32_e32 v152, 6, v185
	v_bfe_u32 v186, v2, 5, 1
	v_mad_i32_i24 v5, v147, s73, v5
	v_ashrrev_i32_e32 v153, 31, v152
	v_ashrrev_i32_e32 v183, 3, v2
	v_lshl_add_u64 v[4:5], v[152:153], 1, v[4:5]
	v_lshlrev_b32_e32 v0, 4, v186
	v_med3_i32 v36, v183, 0, v141
	v_lshlrev_b32_e32 v38, 3, v2
	v_lshl_add_u64 v[24:25], v[4:5], 0, v[0:1]
	v_mul_u32_u24_e32 v36, 0x600, v36
	v_mov_b32_e32 v37, v1
	v_and_b32_e32 v150, 56, v38
	v_add_co_u32_e32 v28, vcc, s74, v24
	v_lshl_add_u64 v[36:37], v[36:37], 1, s[44:45]
	v_lshlrev_b32_e32 v44, 1, v150
	v_mov_b32_e32 v45, v1
	v_lshl_add_u64 v[32:33], v[24:25], 0, s[20:21]
	v_addc_co_u32_e32 v29, vcc, 0, v25, vcc
	v_lshl_add_u64 v[40:41], v[36:37], 0, v[44:45]
	global_load_dwordx4 v[4:7], v[24:25], off
	global_load_dwordx4 v[8:11], v[24:25], off offset:32
	global_load_dwordx4 v[12:15], v[32:33], off offset:32
	global_load_dwordx4 v[16:19], v[32:33], off offset:64
	global_load_dwordx4 v[20:23], v[24:25], off offset:64
	s_nop 0
	global_load_dwordx4 v[24:27], v[24:25], off offset:96
	s_nop 0
	global_load_dwordx4 v[28:31], v[28:29], off
	s_nop 0
	global_load_dwordx4 v[32:35], v[32:33], off offset:96
	s_nop 0
	global_load_dwordx4 v[36:39], v[40:41], off offset:1792
	s_nop 0
	global_load_dwordx4 v[40:43], v[40:41], off offset:1920
	v_or_b32_e32 v148, 32, v146
	v_mov_b32_e32 v149, v147
	v_lshl_add_u64 v[46:47], v[146:147], 2, s[18:19]
	v_lshl_add_u64 v[48:49], v[148:149], 2, s[18:19]
	global_load_dword v187, v[46:47], off
	global_load_dword v188, v[48:49], off
	v_lshlrev_b32_e32 v47, 7, v2
	v_and_b32_e32 v46, 63, v2
	v_lshlrev_b32_e32 v48, 4, v2
	v_mad_i32_i24 v175, v3, s72, 0
	v_and_b32_e32 v3, 0xffffe000, v47
	v_lshlrev_b32_e32 v46, 4, v46
	v_mul_lo_u32 v47, v183, s75
	v_and_b32_e32 v48, 0x70, v48
	v_add_u32_e32 v3, 0, v3
	v_and_b32_e32 v49, 16, v2
	v_lshrrev_b32_e32 v50, 2, v2
	v_mul_u32_u24_e32 v51, 0x90, v151
	v_add3_u32 v140, 0, v47, v48
	v_add_u32_e32 v176, v3, v46
	v_lshlrev_b32_e32 v184, 2, v186
	v_lshlrev_b32_e32 v3, 2, v2
	v_mad_u64_u32 v[142:143], s[0:1], v183, 48, v[140:141]
	v_add3_u32 v178, 0, v51, v0
	v_and_or_b32 v0, v50, 3, v184
	v_and_or_b32 v3, v3, 12, v49
	v_mul_u32_u24_e32 v0, 0xc0, v0
	v_lshlrev_b32_e32 v3, 1, v3
	v_add3_u32 v179, 0, v0, v3
	v_bitop3_b32 v0, v2, 31, v170 bitop3:0xe0
	s_lshl_b32 s84, s61, 2
	v_lshl_add_u64 v[144:145], s[44:45], 0, v[44:45]
	v_mad_u64_u32 v[154:155], s[0:1], v146, s73, 0
	v_sub_u32_e32 v192, v0, v184
	v_mov_b32_e32 v0, v1
	v_mov_b32_e32 v2, v1
	v_mov_b32_e32 v3, v1
	s_mov_b32 s85, 0
	s_add_i32 s83, s84, 4
	v_or_b32_e32 v143, 31, v182
	v_or_b32_e32 v177, 63, v182
	v_mad_i32_i24 v155, v147, s73, v155
	v_add_u32_e32 v190, 0xffffff41, v182
	v_add_u32_e32 v191, 0xffffff61, v182
	v_add_u32_e32 v180, 64, v183
	s_add_i32 s86, s60, 0x100
	v_mov_b32_e32 v193, 0xf149f2ca
	v_mov_b32_e32 v194, 0xf149f2ca
	s_mov_b32 s87, 0
	s_mov_b32 s0, 0
	v_mov_b64_e32 v[156:157], v[0:1]
	s_waitcnt vmcnt(11)
	ds_write_b128 v176, v[4:7] offset:53248
	s_waitcnt vmcnt(10)
	ds_write_b128 v176, v[8:11] offset:54272
	s_waitcnt vmcnt(7)
	ds_write_b128 v176, v[20:23] offset:55296
	s_waitcnt vmcnt(6)
	ds_write_b128 v176, v[24:27] offset:56320
	s_waitcnt vmcnt(5)
	ds_write_b128 v176, v[28:31] offset:57344
	ds_write_b128 v176, v[12:15] offset:58368
	ds_write_b128 v176, v[16:19] offset:59392
	s_waitcnt vmcnt(4)
	ds_write_b128 v176, v[32:35] offset:60416
	s_waitcnt lgkmcnt(0)
	s_barrier
	s_waitcnt vmcnt(3)
	ds_write_b128 v140, v[36:39]
	s_waitcnt vmcnt(2)
	ds_write_b128 v142, v[40:43] offset:18432
	s_waitcnt lgkmcnt(0)
	s_barrier
	ds_read_b32 v189, v175 offset:43524
	v_mov_b32_e32 v16, v1
	v_mov_b32_e32 v17, v1
	v_mov_b32_e32 v4, v1
	v_mov_b32_e32 v5, v1
	v_mov_b32_e32 v6, v1
	v_mov_b32_e32 v7, v1
	v_mov_b32_e32 v8, v1
	v_mov_b32_e32 v9, v1
	v_mov_b32_e32 v10, v1
	v_mov_b32_e32 v11, v1
	v_mov_b32_e32 v12, v1
	v_mov_b32_e32 v13, v1
	v_mov_b32_e32 v14, v1
	v_mov_b32_e32 v15, v1
	v_mov_b64_e32 v[48:49], v[16:17]
	v_mov_b64_e32 v[64:65], v[16:17]
	v_mov_b64_e32 v[32:33], v[16:17]
	v_mov_b64_e32 v[46:47], v[14:15]
	v_mov_b64_e32 v[44:45], v[12:13]
	v_mov_b64_e32 v[42:43], v[10:11]
	v_mov_b64_e32 v[40:41], v[8:9]
	v_mov_b64_e32 v[38:39], v[6:7]
	v_mov_b64_e32 v[36:37], v[4:5]
	v_mov_b64_e32 v[34:35], v[2:3]
	v_mov_b64_e32 v[62:63], v[14:15]
	v_mov_b64_e32 v[60:61], v[12:13]
	v_mov_b64_e32 v[58:59], v[10:11]
	v_mov_b64_e32 v[56:57], v[8:9]
	v_mov_b64_e32 v[54:55], v[6:7]
	v_mov_b64_e32 v[52:53], v[4:5]
	v_mov_b64_e32 v[50:51], v[2:3]
	v_mov_b64_e32 v[30:31], v[14:15]
	v_mov_b64_e32 v[28:29], v[12:13]
	v_mov_b64_e32 v[26:27], v[10:11]
	v_mov_b64_e32 v[24:25], v[8:9]
	v_mov_b64_e32 v[22:23], v[6:7]
	v_mov_b64_e32 v[20:21], v[4:5]
	v_mov_b64_e32 v[18:19], v[2:3]

.Lmoba_skipfill:
	v_and_b32_e32 v253, 32, v200
	v_add_u32_e32 v253, 0x1e000, v253
	v_readfirstlane_b32 s90, v200
	s_cmp_ge_u32 s90, 0x100
	s_cbranch_scc1 .Lprio_moba
	s_setprio 1
.Lprio_moba:
	s_mov_b32 s91, 0x1d094
	s_mov_b32 s32, 0x1d114
	s_xor_b64 s[72:73], s[2:3], -1
	s_and_b64 s[0:1], s[2:3], exec
	s_cselect_b32 s97, s96, s95
	v_ashrrev_i32_e32 v80, 8, v78
	v_lshl_add_u32 v62, s97, 1, v80
	v_and_b32_e32 v81, 0xc0, v78
	v_and_b32_e32 v79, 31, v78
	v_lshl_or_b32 v83, v62, 8, v81
	v_or_b32_e32 v0, v83, v79
	v_ashrrev_i32_e32 v1, 31, v0
	v_lshl_add_u64 v[172:173], s[44:45], 0, v[0:1]
	v_bfe_u32 v82, v78, 5, 1
	v_mad_u64_u32 v[0:1], s[0:1], v172, s84, v[170:171]
	v_mad_i32_i24 v1, v173, s84, v1
	v_lshlrev_b32_e32 v168, 4, v82
	v_lshl_add_u64 v[0:1], v[0:1], 0, v[168:169]
	global_load_dwordx4 v[20:23], v[0:1], off offset:32
	global_load_dwordx4 v[28:31], v[0:1], off
	global_load_dwordx4 v[16:19], v[0:1], off offset:96
	global_load_dwordx4 v[24:27], v[0:1], off offset:64
	v_add_co_u32_e32 v144, vcc, 0x28000, v0
	s_nop 1
	v_addc_co_u32_e32 v145, vcc, 0, v1, vcc
	global_load_dwordx4 v[124:127], v[144:145], off offset:32
	global_load_dwordx4 v[132:135], v[144:145], off
	global_load_dwordx4 v[120:123], v[144:145], off offset:96
	global_load_dwordx4 v[128:131], v[144:145], off offset:64
	v_ashrrev_i32_e32 v146, 3, v200
	v_med3_i32 v146, v146, 0, v201
	v_mul_u32_u24_e32 v146, 0xa00, v146
	v_mov_b32_e32 v147, 0
	v_lshl_add_u64 v[146:147], v[146:147], 1, s[68:69]
	v_lshlrev_b32_e32 v144, 4, v200
	v_and_b32_e32 v144, 0x70, v144
	v_mov_b32_e32 v145, 0
	v_lshl_add_u64 v[146:147], v[146:147], 0, v[144:145]
	global_load_dwordx4 v[136:139], v[146:147], off
	global_load_dwordx4 v[140:143], v[146:147], off offset:1536
	v_and_b32_e32 v0, 32, v78
	v_mov_b32_e32 v1, v169
	v_lshl_add_u64 v[12:13], s[34:35], 0, v[0:1]
	v_mov_b32_e32 v63, 0
	v_lshl_add_u64 v[0:1], v[12:13], 0, s[50:51]
	v_cmp_lt_i32_e32 vcc, 0, v62
	v_mov_b32_e32 v64, 0
	s_waitcnt vmcnt(3)
	v_lshlrev_b32_e32 v15, 16, v20
	s_waitcnt vmcnt(2)
	v_lshlrev_b32_e32 v14, 16, v28
	v_and_b32_e32 v45, 0xffff0000, v20
	v_and_b32_e32 v44, 0xffff0000, v28
	v_lshlrev_b32_e32 v43, 16, v21
	v_lshlrev_b32_e32 v42, 16, v29
	v_and_b32_e32 v41, 0xffff0000, v21
	v_and_b32_e32 v40, 0xffff0000, v29
	v_lshlrev_b32_e32 v39, 16, v22
	v_lshlrev_b32_e32 v38, 16, v30
	v_and_b32_e32 v37, 0xffff0000, v22
	v_and_b32_e32 v36, 0xffff0000, v30
	v_lshlrev_b32_e32 v35, 16, v23
	v_lshlrev_b32_e32 v34, 16, v31
	v_and_b32_e32 v33, 0xffff0000, v23
	v_and_b32_e32 v32, 0xffff0000, v31
	s_waitcnt vmcnt(1)
	v_lshlrev_b32_e32 v49, 16, v16
	s_waitcnt vmcnt(0)
	v_lshlrev_b32_e32 v48, 16, v24
	v_and_b32_e32 v61, 0xffff0000, v16
	v_and_b32_e32 v60, 0xffff0000, v24
	v_lshlrev_b32_e32 v59, 16, v17
	v_lshlrev_b32_e32 v58, 16, v25
	v_and_b32_e32 v57, 0xffff0000, v17
	v_and_b32_e32 v56, 0xffff0000, v25
	v_lshlrev_b32_e32 v55, 16, v18
	v_lshlrev_b32_e32 v54, 16, v26
	v_and_b32_e32 v53, 0xffff0000, v18
	v_and_b32_e32 v52, 0xffff0000, v26
	v_lshlrev_b32_e32 v51, 16, v19
	v_lshlrev_b32_e32 v50, 16, v27
	v_and_b32_e32 v47, 0xffff0000, v19
	v_and_b32_e32 v46, 0xffff0000, v27
	s_and_saveexec_b64 s[2:3], vcc
	s_cbranch_execz .LBB0_1293
	ds_read_b128 v[2:5], v253 offset:0
	ds_read_b128 v[6:9], v253 offset:64
	ds_read_b128 v[64:67], v253 offset:16
	ds_read_b128 v[68:71], v253 offset:80
	ds_read_b128 v[72:75], v253 offset:128
	ds_read_b128 v[84:87], v253 offset:192
	ds_read_b128 v[88:91], v253 offset:144
	ds_read_b128 v[92:95], v253 offset:208
	s_waitcnt lgkmcnt(7)
	v_mov_b32_e32 v10, v2
	s_waitcnt lgkmcnt(6)
	v_mov_b32_e32 v11, v6
	v_mov_b32_e32 v6, v3
	v_pk_mul_f32 v[6:7], v[6:7], v[44:45]
	v_mov_b32_e32 v2, v4
	v_mov_b32_e32 v3, v8
	v_mov_b32_e32 v8, v5
	s_waitcnt lgkmcnt(4)
	v_mov_b32_e32 v5, v68
	v_mov_b32_e32 v68, v65
	v_mov_b32_e32 v65, v70
	v_mov_b32_e32 v70, v67
	s_waitcnt lgkmcnt(2)
	v_mov_b32_e32 v67, v84
	v_mov_b32_e32 v84, v73
	v_pk_fma_f32 v[6:7], v[10:11], v[14:15], v[6:7]
	v_mov_b32_e32 v4, v64
	v_mov_b32_e32 v64, v66
	v_mov_b32_e32 v66, v72
	v_pk_mul_f32 v[84:85], v[84:85], v[60:61]
	v_pk_fma_f32 v[2:3], v[2:3], v[42:43], v[6:7]
	v_mov_b32_e32 v72, v74
	v_mov_b32_e32 v73, v86
	v_pk_fma_f32 v[10:11], v[66:67], v[48:49], v[84:85]
	v_pk_fma_f32 v[2:3], v[8:9], v[40:41], v[2:3]
	v_mov_b32_e32 v86, v75
	v_pk_fma_f32 v[6:7], v[72:73], v[58:59], v[10:11]
	v_pk_fma_f32 v[2:3], v[4:5], v[38:39], v[2:3]
	s_waitcnt lgkmcnt(1)
	v_mov_b32_e32 v74, v88
	s_waitcnt lgkmcnt(0)
	v_mov_b32_e32 v75, v92
	v_pk_fma_f32 v[6:7], v[86:87], v[56:57], v[6:7]
	v_pk_fma_f32 v[2:3], v[68:69], v[36:37], v[2:3]
	v_mov_b32_e32 v92, v89
	v_pk_fma_f32 v[4:5], v[74:75], v[54:55], v[6:7]
	v_pk_fma_f32 v[2:3], v[64:65], v[34:35], v[2:3]
	v_mov_b32_e32 v76, v90
	v_mov_b32_e32 v77, v94
	v_pk_fma_f32 v[4:5], v[92:93], v[52:53], v[4:5]
	v_pk_fma_f32 v[2:3], v[70:71], v[32:33], v[2:3]
	v_mov_b32_e32 v94, v91
	v_pk_fma_f32 v[4:5], v[76:77], v[50:51], v[4:5]
	v_add_f32_e32 v2, 0, v2
	v_add_f32_e32 v6, v2, v3
	v_pk_fma_f32 v[2:3], v[94:95], v[46:47], v[4:5]
	s_nop 0
	v_add_f32_e32 v2, v6, v2
	v_add_f32_e32 v64, v2, v3
